# P1 in-projection GEMM K-loop head pinned at 64-byte phase 16 (padding only)
# speedup vs baseline: 1.0003x; 1.0003x over previous
.LBB0_220:
	s_ashr_i32 s11, s10, 31
	s_lshl_b64 s[12:13], s[10:11], 19
	s_add_u32 s12, s22, s12
	s_addc_u32 s13, s23, s13
	s_and_b64 s[14:15], s[2:3], exec
	s_cselect_b32 s11, s13, s19
	s_cselect_b32 s37, s12, s18
	s_ashr_i32 s9, s8, 31
	s_lshl_b64 s[14:15], s[8:9], 19
	s_add_u32 s14, s24, s14
	s_addc_u32 s15, s25, s15
	s_and_b64 s[20:21], s[2:3], exec
	s_cselect_b32 s9, s15, s17
	s_cselect_b32 s38, s14, s16
	s_add_u32 s39, s16, 0x100
	s_addc_u32 s40, s17, 0
	s_add_u32 s16, s18, 0x40080
	v_mov_b32_e32 v0, 0
	s_addc_u32 s17, s19, 0
	s_mov_b32 s41, -2
	v_mov_b32_e32 v1, v0
	v_mov_b32_e32 v2, v0
	v_mov_b32_e32 v3, v0
	v_mov_b32_e32 v4, v0
	v_mov_b32_e32 v5, v0
	v_mov_b32_e32 v6, v0
	v_mov_b32_e32 v7, v0
	v_mov_b32_e32 v12, v0
	v_mov_b32_e32 v13, v0
	v_mov_b32_e32 v14, v0
	v_mov_b32_e32 v15, v0
	v_mov_b32_e32 v20, v0
	v_mov_b32_e32 v21, v0
	v_mov_b32_e32 v22, v0
	v_mov_b32_e32 v23, v0
	v_mov_b32_e32 v28, v0
	v_mov_b32_e32 v29, v0
	v_mov_b32_e32 v30, v0
	v_mov_b32_e32 v31, v0
	v_mov_b32_e32 v36, v0
	v_mov_b32_e32 v37, v0
	v_mov_b32_e32 v38, v0
	v_mov_b32_e32 v39, v0
	v_mov_b32_e32 v44, v0
	v_mov_b32_e32 v45, v0
	v_mov_b32_e32 v46, v0
	v_mov_b32_e32 v47, v0
	v_mov_b32_e32 v52, v0
	v_mov_b32_e32 v53, v0
	v_mov_b32_e32 v54, v0
	v_mov_b32_e32 v55, v0
	v_mov_b32_e32 v8, v0
	v_mov_b32_e32 v9, v0
	v_mov_b32_e32 v10, v0
	v_mov_b32_e32 v11, v0
	v_mov_b32_e32 v16, v0
	v_mov_b32_e32 v17, v0
	v_mov_b32_e32 v18, v0
	v_mov_b32_e32 v19, v0
	v_mov_b32_e32 v24, v0
	v_mov_b32_e32 v25, v0
	v_mov_b32_e32 v26, v0
	v_mov_b32_e32 v27, v0
	v_mov_b32_e32 v32, v0
	v_mov_b32_e32 v33, v0
	v_mov_b32_e32 v34, v0
	v_mov_b32_e32 v35, v0
	v_mov_b32_e32 v40, v0
	v_mov_b32_e32 v41, v0
	v_mov_b32_e32 v42, v0
	v_mov_b32_e32 v43, v0
	v_mov_b32_e32 v48, v0
	v_mov_b32_e32 v49, v0
	v_mov_b32_e32 v50, v0
	v_mov_b32_e32 v51, v0
	v_mov_b32_e32 v56, v0
	v_mov_b32_e32 v57, v0
	v_mov_b32_e32 v58, v0
	v_mov_b32_e32 v59, v0
	v_mov_b32_e32 v60, v0
	v_mov_b32_e32 v61, v0
	v_mov_b32_e32 v62, v0
	v_mov_b32_e32 v63, v0
	v_mov_b32_e32 v64, v0
	v_mov_b32_e32 v65, v0
	v_mov_b32_e32 v66, v0
	v_mov_b32_e32 v67, v0
	v_mov_b32_e32 v68, v0
	v_mov_b32_e32 v69, v0
	v_mov_b32_e32 v70, v0
	v_mov_b32_e32 v71, v0
	v_mov_b32_e32 v76, v0
	v_mov_b32_e32 v77, v0
	v_mov_b32_e32 v78, v0
	v_mov_b32_e32 v79, v0
	v_mov_b32_e32 v84, v0
	v_mov_b32_e32 v85, v0
	v_mov_b32_e32 v86, v0
	v_mov_b32_e32 v87, v0
	v_mov_b32_e32 v92, v0
	v_mov_b32_e32 v93, v0
	v_mov_b32_e32 v94, v0
	v_mov_b32_e32 v95, v0
	v_mov_b32_e32 v100, v0
	v_mov_b32_e32 v101, v0
	v_mov_b32_e32 v102, v0
	v_mov_b32_e32 v103, v0
	v_mov_b32_e32 v108, v0
	v_mov_b32_e32 v109, v0
	v_mov_b32_e32 v110, v0
	v_mov_b32_e32 v111, v0
	v_mov_b32_e32 v118, v0
	v_mov_b32_e32 v119, v0
	v_mov_b32_e32 v120, v0
	v_mov_b32_e32 v121, v0
	v_mov_b32_e32 v72, v0
	v_mov_b32_e32 v73, v0
	v_mov_b32_e32 v74, v0
	v_mov_b32_e32 v75, v0
	v_mov_b32_e32 v80, v0
	v_mov_b32_e32 v81, v0
	v_mov_b32_e32 v82, v0
	v_mov_b32_e32 v83, v0
	v_mov_b32_e32 v88, v0
	v_mov_b32_e32 v89, v0
	v_mov_b32_e32 v90, v0
	v_mov_b32_e32 v91, v0
	v_mov_b32_e32 v96, v0
	v_mov_b32_e32 v97, v0
	v_mov_b32_e32 v98, v0
	v_mov_b32_e32 v99, v0
	v_mov_b32_e32 v104, v0
	v_mov_b32_e32 v105, v0
	v_mov_b32_e32 v106, v0
	v_mov_b32_e32 v107, v0
	v_mov_b32_e32 v114, v0
	v_mov_b32_e32 v115, v0
	v_mov_b32_e32 v116, v0
	v_mov_b32_e32 v117, v0
	v_mov_b32_e32 v122, v0
	v_mov_b32_e32 v123, v0
	v_mov_b32_e32 v124, v0
	v_mov_b32_e32 v125, v0
	v_mov_b32_e32 v126, v0
	v_mov_b32_e32 v127, v0
	v_mov_b32_e32 v128, v0
	v_mov_b32_e32 v129, v0
	.p2align 6
	s_nop 0
	s_nop 0
	s_nop 0
	s_nop 0

.LBB0_224:
	s_and_b32 s9, s35, -2
	s_cmp_gt_i32 s35, 15
	v_lshl_or_b32 v144, s35, 8, v147
	s_cselect_b64 vcc, -1, 0
	s_cmp_lg_u32 s9, 4
	v_lshl_add_u32 v149, s36, 8, v141
	v_cndmask_b32_e32 v140, 1.0, v230, vcc
	s_cselect_b64 vcc, -1, 0
	v_ashrrev_i32_e32 v145, 31, v144
	v_mov_b64_e32 v[142:143], s[4:5]
	v_cndmask_b32_e32 v140, v231, v140, vcc
	v_mad_i64_i32 v[150:151], s[16:17], v149, s97, v[142:143]
	v_lshlrev_b64 v[144:145], 1, v[144:145]
	v_lshl_add_u64 v[150:151], v[150:151], 0, v[144:145]
	v_pk_mul_f32 v[128:129], v[140:141], v[128:129] op_sel_hi:[0,1]
	v_pk_mul_f32 v[126:127], v[140:141], v[126:127] op_sel_hi:[0,1]
	v_pk_mul_f32 v[152:153], v[140:141], v[124:125] op_sel_hi:[0,1]
	v_pk_mul_f32 v[124:125], v[140:141], v[122:123] op_sel_hi:[0,1]
	v_cvt_pk_bf16_f32 v122, v126, v127
	v_cvt_pk_bf16_f32 v123, v128, v129
	v_cvt_pk_bf16_f32 v124, v124, v125
	v_cvt_pk_bf16_f32 v125, v152, v153
	global_store_dwordx4 v[150:151], v[122:125], off
	v_pk_mul_f32 v[118:119], v[140:141], v[118:119] op_sel_hi:[0,1]
	v_pk_mul_f32 v[120:121], v[140:141], v[120:121] op_sel_hi:[0,1]
	v_pk_mul_f32 v[122:123], v[140:141], v[110:111] op_sel_hi:[0,1]
	v_pk_mul_f32 v[110:111], v[140:141], v[108:109] op_sel_hi:[0,1]
	v_cvt_pk_bf16_f32 v108, v118, v119
	v_cvt_pk_bf16_f32 v109, v120, v121
	v_cvt_pk_bf16_f32 v110, v110, v111
	v_cvt_pk_bf16_f32 v111, v122, v123
	global_store_dwordx4 v[150:151], v[108:111], off offset:256
	v_pk_mul_f32 v[114:115], v[140:141], v[114:115] op_sel_hi:[0,1]
	v_pk_mul_f32 v[100:101], v[140:141], v[100:101] op_sel_hi:[0,1]
	v_or_b32_e32 v108, 16, v149
	v_mad_i64_i32 v[108:109], s[16:17], v108, s97, v[142:143]
	v_lshl_add_u64 v[108:109], v[108:109], 0, v[144:145]
	v_pk_mul_f32 v[110:111], v[140:141], v[116:117] op_sel_hi:[0,1]
	v_pk_mul_f32 v[116:117], v[140:141], v[106:107] op_sel_hi:[0,1]
	v_pk_mul_f32 v[106:107], v[140:141], v[104:105] op_sel_hi:[0,1]
	v_cvt_pk_bf16_f32 v104, v114, v115
	v_cvt_pk_bf16_f32 v105, v110, v111
	v_cvt_pk_bf16_f32 v106, v106, v107
	v_cvt_pk_bf16_f32 v107, v116, v117
	global_store_dwordx4 v[108:109], v[104:107], off
	v_pk_mul_f32 v[102:103], v[140:141], v[102:103] op_sel_hi:[0,1]
	v_pk_mul_f32 v[96:97], v[140:141], v[96:97] op_sel_hi:[0,1]
	v_pk_mul_f32 v[104:105], v[140:141], v[94:95] op_sel_hi:[0,1]
	v_pk_mul_f32 v[94:95], v[140:141], v[92:93] op_sel_hi:[0,1]
	v_cvt_pk_bf16_f32 v92, v100, v101
	v_cvt_pk_bf16_f32 v93, v102, v103
	v_cvt_pk_bf16_f32 v94, v94, v95
	v_cvt_pk_bf16_f32 v95, v104, v105
	global_store_dwordx4 v[108:109], v[92:95], off offset:256
	v_pk_mul_f32 v[84:85], v[140:141], v[84:85] op_sel_hi:[0,1]
	v_pk_mul_f32 v[86:87], v[140:141], v[86:87] op_sel_hi:[0,1]
	v_or_b32_e32 v92, 32, v149
	v_mad_i64_i32 v[92:93], s[16:17], v92, s97, v[142:143]
	v_lshl_add_u64 v[92:93], v[92:93], 0, v[144:145]
	v_pk_mul_f32 v[94:95], v[140:141], v[98:99] op_sel_hi:[0,1]
	v_pk_mul_f32 v[98:99], v[140:141], v[90:91] op_sel_hi:[0,1]
	v_pk_mul_f32 v[90:91], v[140:141], v[88:89] op_sel_hi:[0,1]
	v_cvt_pk_bf16_f32 v88, v96, v97
	v_cvt_pk_bf16_f32 v89, v94, v95
	v_cvt_pk_bf16_f32 v90, v90, v91
	v_cvt_pk_bf16_f32 v91, v98, v99
	global_store_dwordx4 v[92:93], v[88:91], off
	v_pk_mul_f32 v[80:81], v[140:141], v[80:81] op_sel_hi:[0,1]
	v_pk_mul_f32 v[68:69], v[140:141], v[68:69] op_sel_hi:[0,1]
	v_pk_mul_f32 v[88:89], v[140:141], v[78:79] op_sel_hi:[0,1]
	v_pk_mul_f32 v[78:79], v[140:141], v[76:77] op_sel_hi:[0,1]
	v_cvt_pk_bf16_f32 v76, v84, v85
	v_cvt_pk_bf16_f32 v77, v86, v87
	v_cvt_pk_bf16_f32 v78, v78, v79
	v_cvt_pk_bf16_f32 v79, v88, v89
	global_store_dwordx4 v[92:93], v[76:79], off offset:256
	v_pk_mul_f32 v[70:71], v[140:141], v[70:71] op_sel_hi:[0,1]
	v_pk_mul_f32 v[62:63], v[140:141], v[62:63] op_sel_hi:[0,1]
	v_or_b32_e32 v76, 48, v149
	v_mad_i64_i32 v[76:77], s[16:17], v76, s97, v[142:143]
	v_lshl_add_u64 v[76:77], v[76:77], 0, v[144:145]
	v_pk_mul_f32 v[78:79], v[140:141], v[82:83] op_sel_hi:[0,1]
	v_pk_mul_f32 v[82:83], v[140:141], v[74:75] op_sel_hi:[0,1]
	v_pk_mul_f32 v[74:75], v[140:141], v[72:73] op_sel_hi:[0,1]
	v_cvt_pk_bf16_f32 v72, v80, v81
	v_cvt_pk_bf16_f32 v73, v78, v79
	v_cvt_pk_bf16_f32 v74, v74, v75
	v_cvt_pk_bf16_f32 v75, v82, v83
	global_store_dwordx4 v[76:77], v[72:75], off
	v_pk_mul_f32 v[60:61], v[140:141], v[60:61] op_sel_hi:[0,1]
	v_pk_mul_f32 v[52:53], v[140:141], v[52:53] op_sel_hi:[0,1]
	v_pk_mul_f32 v[72:73], v[140:141], v[66:67] op_sel_hi:[0,1]
	v_pk_mul_f32 v[66:67], v[140:141], v[64:65] op_sel_hi:[0,1]
	v_cvt_pk_bf16_f32 v64, v68, v69
	v_cvt_pk_bf16_f32 v65, v70, v71
	v_cvt_pk_bf16_f32 v66, v66, v67
	v_cvt_pk_bf16_f32 v67, v72, v73
	global_store_dwordx4 v[76:77], v[64:67], off offset:256
	v_pk_mul_f32 v[54:55], v[140:141], v[54:55] op_sel_hi:[0,1]
	v_pk_mul_f32 v[48:49], v[140:141], v[48:49] op_sel_hi:[0,1]
	v_add_u32_e32 v64, 0x80, v149
	v_mad_i64_i32 v[64:65], s[16:17], v64, s97, v[142:143]
	v_lshl_add_u64 v[64:65], v[64:65], 0, v[144:145]
	v_pk_mul_f32 v[66:67], v[140:141], v[58:59] op_sel_hi:[0,1]
	v_pk_mul_f32 v[58:59], v[140:141], v[56:57] op_sel_hi:[0,1]
	v_cvt_pk_bf16_f32 v56, v60, v61
	v_cvt_pk_bf16_f32 v57, v62, v63
	v_cvt_pk_bf16_f32 v58, v58, v59
	v_cvt_pk_bf16_f32 v59, v66, v67
	global_store_dwordx4 v[64:65], v[56:59], off
	v_pk_mul_f32 v[36:37], v[140:141], v[36:37] op_sel_hi:[0,1]
	v_pk_mul_f32 v[38:39], v[140:141], v[38:39] op_sel_hi:[0,1]
	v_pk_mul_f32 v[56:57], v[140:141], v[46:47] op_sel_hi:[0,1]
	v_pk_mul_f32 v[46:47], v[140:141], v[44:45] op_sel_hi:[0,1]
	v_cvt_pk_bf16_f32 v44, v52, v53
	v_cvt_pk_bf16_f32 v45, v54, v55
	v_cvt_pk_bf16_f32 v46, v46, v47
	v_cvt_pk_bf16_f32 v47, v56, v57
	global_store_dwordx4 v[64:65], v[44:47], off offset:256
	v_pk_mul_f32 v[32:33], v[140:141], v[32:33] op_sel_hi:[0,1]
	v_pk_mul_f32 v[20:21], v[140:141], v[20:21] op_sel_hi:[0,1]
	v_add_u32_e32 v44, 0x90, v149
	v_mad_i64_i32 v[44:45], s[16:17], v44, s97, v[142:143]
	v_lshl_add_u64 v[44:45], v[44:45], 0, v[144:145]
	v_pk_mul_f32 v[46:47], v[140:141], v[50:51] op_sel_hi:[0,1]
	v_pk_mul_f32 v[50:51], v[140:141], v[42:43] op_sel_hi:[0,1]
	v_pk_mul_f32 v[42:43], v[140:141], v[40:41] op_sel_hi:[0,1]
	v_cvt_pk_bf16_f32 v40, v48, v49
	v_cvt_pk_bf16_f32 v41, v46, v47
	v_cvt_pk_bf16_f32 v42, v42, v43
	v_cvt_pk_bf16_f32 v43, v50, v51
	global_store_dwordx4 v[44:45], v[40:43], off
	v_pk_mul_f32 v[22:23], v[140:141], v[22:23] op_sel_hi:[0,1]
	v_pk_mul_f32 v[16:17], v[140:141], v[16:17] op_sel_hi:[0,1]
	v_pk_mul_f32 v[40:41], v[140:141], v[30:31] op_sel_hi:[0,1]
	v_pk_mul_f32 v[30:31], v[140:141], v[28:29] op_sel_hi:[0,1]
	v_cvt_pk_bf16_f32 v28, v36, v37
	v_cvt_pk_bf16_f32 v29, v38, v39
	v_cvt_pk_bf16_f32 v30, v30, v31
	v_cvt_pk_bf16_f32 v31, v40, v41
	global_store_dwordx4 v[44:45], v[28:31], off offset:256
	s_andn2_b64 vcc, exec, s[2:3]
	s_mov_b64 s[2:3], -1
	v_add_u32_e32 v28, 0xa0, v149
	v_mad_i64_i32 v[28:29], s[16:17], v28, s97, v[142:143]
	v_lshl_add_u64 v[28:29], v[28:29], 0, v[144:145]
	v_pk_mul_f32 v[30:31], v[140:141], v[34:35] op_sel_hi:[0,1]
	v_pk_mul_f32 v[34:35], v[140:141], v[26:27] op_sel_hi:[0,1]
	v_pk_mul_f32 v[26:27], v[140:141], v[24:25] op_sel_hi:[0,1]
	v_cvt_pk_bf16_f32 v24, v32, v33
	v_cvt_pk_bf16_f32 v25, v30, v31
	v_cvt_pk_bf16_f32 v26, v26, v27
	v_cvt_pk_bf16_f32 v27, v34, v35
	global_store_dwordx4 v[28:29], v[24:27], off
	v_readlane_b32 s38, v253, 49
	s_movk_i32 s39, 0x4200
	v_pk_mul_f32 v[24:25], v[140:141], v[14:15] op_sel_hi:[0,1]
	v_pk_mul_f32 v[14:15], v[140:141], v[12:13] op_sel_hi:[0,1]
	v_cvt_pk_bf16_f32 v12, v20, v21
	v_cvt_pk_bf16_f32 v13, v22, v23
	v_cvt_pk_bf16_f32 v14, v14, v15
	v_cvt_pk_bf16_f32 v15, v24, v25
	global_store_dwordx4 v[28:29], v[12:15], off offset:256
	v_pk_mul_f32 v[6:7], v[140:141], v[6:7] op_sel_hi:[0,1]
	v_pk_mul_f32 v[4:5], v[140:141], v[4:5] op_sel_hi:[0,1]
	v_add_u32_e32 v12, 0xb0, v149
	v_mad_i64_i32 v[12:13], s[16:17], v12, s97, v[142:143]
	v_lshl_add_u64 v[12:13], v[12:13], 0, v[144:145]
	v_pk_mul_f32 v[14:15], v[140:141], v[18:19] op_sel_hi:[0,1]
	v_pk_mul_f32 v[18:19], v[140:141], v[10:11] op_sel_hi:[0,1]
	v_pk_mul_f32 v[10:11], v[140:141], v[8:9] op_sel_hi:[0,1]
	v_cvt_pk_bf16_f32 v8, v16, v17
	v_cvt_pk_bf16_f32 v9, v14, v15
	v_cvt_pk_bf16_f32 v10, v10, v11
	v_cvt_pk_bf16_f32 v11, v18, v19
	global_store_dwordx4 v[12:13], v[8:11], off
	s_nop 1
	v_pk_mul_f32 v[8:9], v[140:141], v[2:3] op_sel_hi:[0,1]
	v_pk_mul_f32 v[2:3], v[140:141], v[0:1] op_sel_hi:[0,1]
	v_cvt_pk_bf16_f32 v0, v4, v5
	v_cvt_pk_bf16_f32 v1, v6, v7
	v_cvt_pk_bf16_f32 v2, v2, v3
	v_cvt_pk_bf16_f32 v3, v8, v9
	global_store_dwordx4 v[12:13], v[0:3], off offset:256
	s_cbranch_vccnz .LBB0_217
	s_andn2_b64 vcc, exec, s[0:1]
	s_cbranch_vccnz .LBB0_216
	s_barrier
	s_branch .LBB0_216
	.p2align 6
	s_nop 0
	s_nop 0
	s_nop 0
	s_nop 0
	s_nop 0
	s_nop 0
	s_nop 0
